# byte-phase pads: s_nop padding at entry and in unreachable spots so the four GEMM main loops and the attention loop sit at their baseline byte phase mod 64 (entry insert had shifted the whole stream b
# speedup vs baseline: 1.0131x; 1.0004x over previous
; #define LAS __attribute__((address_space(3)))
; __global__ void __launch_bounds__(NWAVES * 64, 2) trunk_fwd(Args args) {
;     extern __shared__ __attribute__((aligned(16))) unsigned char lds_raw[];
;     LAS unsigned char* lds = (LAS unsigned char*)lds_raw;
;     const int Gk = gridDim.x, bx = blockIdx.x;
;     const int vcu = (Gk % 8 == 0) ? (bx % 8) * (Gk / 8) + bx / 8 : bx;
;     unsigned char* ws = args.ws;
;     float* X = args.out;
;     bf16* XB = (bf16*)(ws + WS_XB);
;     float* SS = (float*)(ws + WS_SS);
;     const float* ROPE = (const float*)(ws + WS_ROPE);
;     bf16* ACT0 = (bf16*)(ws + WS_ACT);
;     bf16* ACT1 = ACT0 + (size_t)M * DM;
;     bf16* ACT2 = ACT1 + (size_t)M * DM;
;     bf16* ACT3 = ACT2 + (size_t)M * DM;
;     ...
;     volatile LAS unsigned* MISC = (volatile LAS unsigned*)(lds + 147200);
;     if (threadIdx.x < 32) MISC[threadIdx.x] = 0u;
_Z9trunk_fwd4Args:
	s_mov_b32 s101, 0
	s_nop 0
	s_nop 0
	s_nop 0
	s_nop 0
	s_nop 0
	s_nop 0
	s_nop 0
	s_nop 0
	s_nop 0
	s_nop 0
	s_nop 0
	s_nop 0
	s_nop 0
	s_nop 0
	s_nop 0
	s_load_dword s4, s[0:1], 0x88
	s_load_dwordx2 s[66:67], s[0:1], 0x80
	s_mov_b32 s64, s2
	s_add_u32 s2, s0, 0x88
	s_addc_u32 s3, s1, 0
	s_mov_b32 s90, s64
	v_writelane_b32 v253, s2, 0
	s_nop 1
	v_writelane_b32 v253, s3, 1
	s_waitcnt lgkmcnt(0)
	s_and_b32 s2, s4, 7
	v_writelane_b32 v253, s4, 2
	s_cmp_lg_u32 s2, 0
	s_cbranch_scc0 .LBB0_636
	s_load_dwordx16 s[48:63], s[0:1], 0x40
	v_cmp_gt_u32_e32 vcc, 32, v0
	s_and_saveexec_b64 s[4:5], vcc

; __device__ __forceinline__ int opaque_tid() { int t = threadIdx.x; asm volatile("" : "+v"(t)); return t; }
; __device__ __forceinline__ u32x4 pack8(f32x4 a, f32x4 b) { u32x4 w; w.x = cvt_pk_bf16(a[0], a[1]); w.y = cvt_pk_bf16(a[2], a[3]); w.z = cvt_pk_bf16(b[0], b[1]); w.w = cvt_pk_bf16(b[2], b[3]); return w; }
; __device__ __forceinline__ bf16x8 pack8(f32x4 a, f32x4 b) { u32x4 w = {cvtpk(a[0], a[1]), cvtpk(a[2], a[3]), cvtpk(b[0], b[1]), cvtpk(b[2], b[3])}; return *reinterpret_cast<bf16x8*>(&w); }
; __device__ __forceinline__ void stage_kmean(char* lds, const float* km) {
;     const int tid = opaque_tid(), row = tid >> 4, chunk = tid & 15;
;     const float* kp = km + (row & 15) * 128 + chunk * 8;
;     f32x4 a = *(const f32x4*)kp, b = *(const f32x4*)(kp + 4);
;     a = a * (1.0f / 256.0f); b = b * (1.0f / 256.0f);
;     const bf16x8 h = pack8(a, b);
;     f32x4 ah, bh;
; #pragma unroll
;     for (int j = 0; j < 4; ++j) { ah[j] = __uint_as_float(((unsigned)(unsigned short)h[j]) << 16); bh[j] = __uint_as_float(((unsigned)(unsigned short)h[4 + j]) << 16); }
;     const bf16x8 l = pack8(a - ah, b - bh);
;     *(bf16x8*)(lds + KM_LDS_OFF + row * KM_PITCH + chunk * 16) = (row >= 16) ? l : h;
; }
; __device__ __forceinline__ void moba_phase(char* lds, const bf16* Q, const bf16* K, const bf16* V, bf16* O, const float* kmean, int vcu, int G) {
;     ...
;         if (passn == 0) { stage_kmean(lds, nxt.km); __syncthreads(); }
.LBB0_243:
	s_or_b64 exec, exec, s[0:1]
	s_and_b64 vcc, exec, s[36:37]
	s_mov_b64 s[0:1], -1
	s_waitcnt lgkmcnt(0)
	s_barrier
	s_cbranch_vccnz .LBB0_79
	s_andn2_b64 vcc, exec, s[10:11]
	s_cbranch_vccnz .LBB0_78
	v_mov_b32_e32 v2, v0
	s_mov_b32 s0, 0x3b800000
	v_ashrrev_i32_e32 v18, 4, v2
	v_and_b32_e32 v19, 15, v2
	v_lshlrev_b32_e32 v2, 9, v18
	v_and_b32_e32 v98, 0x1e00, v2
	v_lshl_add_u64 v[2:3], s[18:19], 0, v[98:99]
	v_lshlrev_b32_e32 v98, 5, v19
	v_lshl_add_u64 v[6:7], v[2:3], 0, v[98:99]
	global_load_dwordx4 v[2:5], v[6:7], off offset:16
	s_nop 0
	global_load_dwordx4 v[6:9], v[6:7], off
	v_cmp_lt_i32_e32 vcc, 15, v18
	s_waitcnt vmcnt(1)
	v_pk_mul_f32 v[14:15], v[4:5], s[0:1] op_sel_hi:[1,0]
	s_waitcnt vmcnt(0)
	v_pk_mul_f32 v[10:11], v[8:9], s[0:1] op_sel_hi:[1,0]
	v_pk_mul_f32 v[12:13], v[6:7], s[0:1] op_sel_hi:[1,0]
	v_pk_mul_f32 v[16:17], v[2:3], s[0:1] op_sel_hi:[1,0]
	v_cvt_pk_bf16_f32 v12, v12, v13
	v_cvt_pk_bf16_f32 v13, v10, v11
	s_nop 0
	v_lshlrev_b32_e32 v10, 16, v13
	v_and_b32_e32 v11, 0xffff0000, v13
	v_lshlrev_b32_e32 v21, 16, v12
	v_and_b32_e32 v22, 0xffff0000, v12
	v_xor_b32_e32 v11, 0x80000000, v11
	v_xor_b32_e32 v10, 0x80000000, v10
	v_cvt_pk_bf16_f32 v16, v16, v17
	v_cvt_pk_bf16_f32 v14, v14, v15
	v_pk_fma_f32 v[8:9], v[8:9], s[0:1], v[10:11] op_sel_hi:[1,0,1]
	v_lshlrev_b32_e32 v20, 16, v14
	v_and_b32_e32 v23, 0xffff0000, v14
	v_xor_b32_e32 v11, 0x80000000, v22
	v_xor_b32_e32 v10, 0x80000000, v21
	v_lshlrev_b32_e32 v15, 16, v16
	v_and_b32_e32 v17, 0xffff0000, v16
	v_pk_fma_f32 v[6:7], v[6:7], s[0:1], v[10:11] op_sel_hi:[1,0,1]
	v_xor_b32_e32 v11, 0x80000000, v23
	v_xor_b32_e32 v10, 0x80000000, v20
	v_pk_fma_f32 v[4:5], v[4:5], s[0:1], v[10:11] op_sel_hi:[1,0,1]
	v_xor_b32_e32 v11, 0x80000000, v17
	v_xor_b32_e32 v10, 0x80000000, v15
	v_pk_fma_f32 v[2:3], v[2:3], s[0:1], v[10:11] op_sel_hi:[1,0,1]
	v_cvt_pk_bf16_f32 v6, v6, v7
	v_cvt_pk_bf16_f32 v7, v8, v9
	s_movk_i32 s0, 0x110
	v_cvt_pk_bf16_f32 v8, v2, v3
	v_cvt_pk_bf16_f32 v2, v4, v5
	v_cndmask_b32_e32 v3, v13, v7, vcc
	v_cndmask_b32_e32 v5, v14, v2, vcc
	v_cndmask_b32_e32 v2, v12, v6, vcc
	v_mul_lo_u32 v6, v18, s0
	v_lshlrev_b32_e32 v7, 4, v19
	v_readlane_b32 s0, v255, 35
	v_cndmask_b32_e32 v4, v16, v8, vcc
	s_nop 0
	v_add3_u32 v6, s0, v6, v7
	ds_write_b128 v6, v[2:5]
	s_waitcnt lgkmcnt(0)
	s_barrier
	s_branch .LBB0_78
	s_nop 0
	s_nop 0
	s_nop 0
	s_nop 0
	s_nop 0
	s_nop 0
	s_nop 0
	s_nop 0
	s_nop 0
	s_nop 0
	s_nop 0
	s_nop 0
	s_nop 0

; __device__ __forceinline__ f32x4 ld4bf(const bf16* p) { const v2u w = *(const v2u*)p; return (f32x4){bf_lo(w.x), bf_hi(w.x), bf_lo(w.y), bf_hi(w.y)}; }
; __device__ __forceinline__ void pool_prep(const bf16* X, const float* ss, const float* gain, bf16* PB, LAS unsigned char* lds, int vcu, int G, int tid) {
;     ...
;     for (int chunk = vcu; chunk < M / 64; chunk += G) {
;         const int r0 = chunk * 64, bstart = r0 & ~(SEQ - 1);
;         __syncthreads();
;         if (tid < 80) { const int row = r0 - 16 + tid; rsl[tid] = (row >= bstart) ? pg8::row_rstd(ss, row) : 0.f; }
;         __syncthreads();
;         const int q = tid & 255, half = tid >> 8, w = 2 << (q >> 6);
;         const f32x4 gn = *(const f32x4*)(gain + 4 * q);
;         const int ra = r0 + 32 * half;
;         const bf16* xp = X + 4 * q;
;         f32x4 S = {0.f, 0.f, 0.f, 0.f};
; #pragma unroll
;         for (int j = 1; j <= 16; ++j) { const int row = ra - j; if (j <= w && row >= bstart) S += ld4bf(xp + (size_t)row * DM) * rsl[row - r0 + 16]; }
.Lmy_pool_w2:
	s_mov_b32 s0, 4096
	v_subrev_co_u32_e32 v198, vcc, s0, v22
	s_nop 1
	v_subbrev_co_u32_e32 v199, vcc, 0, v23, vcc
	s_mov_b64 s[0:1], 0x1000
	global_load_dwordx2 v[100:101], v[198:199], off
	global_load_dwordx2 v[102:103], v[198:199], off offset:2048
	v_lshl_add_u64 v[198:199], v[198:199], 0, s[0:1]
	global_load_dwordx2 v[104:105], v[198:199], off
	global_load_dwordx2 v[106:107], v[198:199], off offset:2048
	v_lshl_add_u64 v[198:199], v[198:199], 0, s[0:1]
	global_load_dwordx2 v[108:109], v[198:199], off
	global_load_dwordx2 v[110:111], v[198:199], off offset:2048
	v_lshl_add_u64 v[198:199], v[198:199], 0, s[0:1]
	global_load_dwordx2 v[112:113], v[198:199], off
	global_load_dwordx2 v[114:115], v[198:199], off offset:2048
	v_lshl_add_u64 v[198:199], v[198:199], 0, s[0:1]
	global_load_dwordx2 v[116:117], v[198:199], off
	global_load_dwordx2 v[118:119], v[198:199], off offset:2048
	v_lshl_add_u64 v[198:199], v[198:199], 0, s[0:1]
	global_load_dwordx2 v[120:121], v[198:199], off
	global_load_dwordx2 v[122:123], v[198:199], off offset:2048
	v_lshl_add_u64 v[198:199], v[198:199], 0, s[0:1]
	global_load_dwordx2 v[124:125], v[198:199], off
	global_load_dwordx2 v[126:127], v[198:199], off offset:2048
	v_lshl_add_u64 v[198:199], v[198:199], 0, s[0:1]
	global_load_dwordx2 v[128:129], v[198:199], off
	global_load_dwordx2 v[130:131], v[198:199], off offset:2048
	v_lshl_add_u64 v[198:199], v[198:199], 0, s[0:1]
	global_load_dwordx2 v[132:133], v[198:199], off
	global_load_dwordx2 v[134:135], v[198:199], off offset:2048
	v_lshl_add_u64 v[198:199], v[198:199], 0, s[0:1]
	global_load_dwordx2 v[136:137], v[198:199], off
	global_load_dwordx2 v[138:139], v[198:199], off offset:2048
	v_lshl_add_u64 v[198:199], v[198:199], 0, s[0:1]
	global_load_dwordx2 v[140:141], v[198:199], off
	global_load_dwordx2 v[142:143], v[198:199], off offset:2048
	v_lshl_add_u64 v[198:199], v[198:199], 0, s[0:1]
	global_load_dwordx2 v[144:145], v[198:199], off
	global_load_dwordx2 v[146:147], v[198:199], off offset:2048
	v_lshl_add_u64 v[198:199], v[198:199], 0, s[0:1]
	global_load_dwordx2 v[148:149], v[198:199], off
	global_load_dwordx2 v[150:151], v[198:199], off offset:2048
	v_lshl_add_u64 v[198:199], v[198:199], 0, s[0:1]
	global_load_dwordx2 v[152:153], v[198:199], off
	global_load_dwordx2 v[154:155], v[198:199], off offset:2048
	v_lshl_add_u64 v[198:199], v[198:199], 0, s[0:1]
	global_load_dwordx2 v[156:157], v[198:199], off
	global_load_dwordx2 v[158:159], v[198:199], off offset:2048
	v_lshl_add_u64 v[198:199], v[198:199], 0, s[0:1]
	global_load_dwordx2 v[160:161], v[198:199], off
	global_load_dwordx2 v[162:163], v[198:199], off offset:2048
	v_lshl_add_u64 v[198:199], v[198:199], 0, s[0:1]
	global_load_dwordx2 v[164:165], v[198:199], off
	global_load_dwordx2 v[166:167], v[198:199], off offset:2048
	ds_read_b32 v40, v21 offset:56
	ds_read_b32 v41, v21 offset:60
	ds_read_b32 v42, v21 offset:64
	ds_read_b32 v43, v21 offset:68
	ds_read_b32 v44, v21 offset:72
	ds_read_b32 v45, v21 offset:76
	ds_read_b32 v46, v21 offset:80
	ds_read_b32 v47, v21 offset:84
	ds_read_b32 v48, v21 offset:88
	ds_read_b32 v49, v21 offset:92
	ds_read_b32 v50, v21 offset:96
	ds_read_b32 v51, v21 offset:100
	s_waitcnt lgkmcnt(0)
	ds_read_b32 v52, v21 offset:104
	ds_read_b32 v53, v21 offset:108
	ds_read_b32 v54, v21 offset:112
	ds_read_b32 v55, v21 offset:116
	ds_read_b32 v56, v21 offset:120
	ds_read_b32 v57, v21 offset:124
	ds_read_b32 v58, v21 offset:128
	ds_read_b32 v59, v21 offset:132
	ds_read_b32 v60, v21 offset:136
	ds_read_b32 v61, v21 offset:140
	ds_read_b32 v62, v21 offset:144
	ds_read_b32 v63, v21 offset:148
	s_waitcnt lgkmcnt(0)
	ds_read_b32 v64, v21 offset:152
	ds_read_b32 v65, v21 offset:156
	ds_read_b32 v66, v21 offset:160
	ds_read_b32 v67, v21 offset:164
	ds_read_b32 v68, v21 offset:168
	ds_read_b32 v69, v21 offset:172
	ds_read_b32 v70, v21 offset:176
	ds_read_b32 v71, v21 offset:180
	ds_read_b32 v72, v21 offset:184
	ds_read_b32 v73, v21 offset:188
	v_div_scale_f32 v26, s[0:1], v196, v196, 1.0
	v_rcp_f32_e32 v27, v26
	s_nop 0
	v_fma_f32 v28, -v26, v27, 1.0
	v_fmac_f32_e32 v27, v28, v27
	v_div_scale_f32 v28, vcc, 1.0, v196, 1.0
	v_mul_f32_e32 v29, v28, v27
	v_fma_f32 v30, -v26, v29, v28
	v_fmac_f32_e32 v29, v30, v27
	v_fma_f32 v26, -v26, v29, v28
	s_nop 1
	v_div_fmas_f32 v197, v26, v27, v29
	v_div_fixup_f32 v197, v197, v196, 1.0
	v_mov_b32_e32 v6, 0
	v_mov_b32_e32 v7, 0
	v_mov_b32_e32 v8, 0
	v_mov_b32_e32 v9, 0
	s_waitcnt lgkmcnt(0)
	s_waitcnt vmcnt(32)
	v_cndmask_b32_e64 v100, v100, 0, s[6:7]
	v_cndmask_b32_e64 v101, v101, 0, s[6:7]
	v_cndmask_b32_e64 v102, v102, 0, s[6:7]
	v_cndmask_b32_e64 v103, v103, 0, s[6:7]
	v_lshlrev_b32_e32 v200, 16, v102
	v_and_b32_e32 v201, 0xffff0000, v102
	v_lshlrev_b32_e32 v202, 16, v103
	v_and_b32_e32 v203, 0xffff0000, v103
	v_fma_f32 v6, v41, v200, v6
	v_fma_f32 v7, v41, v201, v7
	v_fma_f32 v8, v41, v202, v8
	v_fma_f32 v9, v41, v203, v9
	v_lshlrev_b32_e32 v200, 16, v100
	v_and_b32_e32 v201, 0xffff0000, v100
	v_lshlrev_b32_e32 v202, 16, v101
	v_and_b32_e32 v203, 0xffff0000, v101
	v_fma_f32 v6, v40, v200, v6
	v_fma_f32 v7, v40, v201, v7
	v_fma_f32 v8, v40, v202, v8
	v_fma_f32 v9, v40, v203, v9
	s_waitcnt vmcnt(31)
; __device__ __forceinline__ unsigned pk2(float lo, float hi) { return pg8::cvt_pk_bf16(lo, hi); }
; __device__ __forceinline__ f32x4 ld4bf(const bf16* p) { const v2u w = *(const v2u*)p; return (f32x4){bf_lo(w.x), bf_hi(w.x), bf_lo(w.y), bf_hi(w.y)}; }
; __device__ __forceinline__ void pool_prep(const bf16* X, const float* ss, const float* gain, bf16* PB, LAS unsigned char* lds, int vcu, int G, int tid) {
;     ...
;         for (int i = 0; i < 32; ++i) { const int row = ra + i, t = row - bstart;
;             const f32x4 xn = ld4bf(xp + (size_t)row * DM) * rsl[row - r0 + 16];
;             f32x4 old = {0.f, 0.f, 0.f, 0.f};
;             if (t >= w) old = ld4bf(xp + (size_t)(row - w) * DM) * rsl[row - w - r0 + 16];
;             S = S + xn - old;
;             const int cnt = (t + 1 < w) ? t + 1 : w;
;             const f32x4 p = (S * (1.0f / (float)cnt) - xn) * gn;
;             v2u o; o.x = pk2(p[0], p[1]); o.y = pk2(p[2], p[3]); *(v2u*)(PB + (size_t)row * DM + 4 * q) = o; }
	v_lshlrev_b32_e32 v200, 16, v104
	v_and_b32_e32 v201, 0xffff0000, v104
	v_lshlrev_b32_e32 v202, 16, v105
	v_and_b32_e32 v203, 0xffff0000, v105
	v_mul_f32_e32 v204, v42, v200
	v_mul_f32_e32 v205, v42, v201
	v_mul_f32_e32 v206, v42, v202
	v_mul_f32_e32 v207, v42, v203
	v_fma_f32 v6, v42, v200, v6
	v_fma_f32 v7, v42, v201, v7
	v_fma_f32 v8, v42, v202, v8
	v_fma_f32 v9, v42, v203, v9
	v_lshlrev_b32_e32 v88, 16, v100
	v_and_b32_e32 v89, 0xffff0000, v100
	v_lshlrev_b32_e32 v90, 16, v101
	v_and_b32_e32 v91, 0xffff0000, v101
	v_mul_f32_e32 v88, v40, v88
	v_mul_f32_e32 v89, v40, v89
	v_mul_f32_e32 v90, v40, v90
	v_mul_f32_e32 v91, v40, v91
	v_sub_f32_e32 v6, v6, v88
	v_sub_f32_e32 v7, v7, v89
	v_sub_f32_e32 v8, v8, v90
	v_sub_f32_e32 v9, v9, v91
	v_add_u32_e32 v92, 1, v20
	v_min_i32_e32 v92, v92, v32
	v_cvt_f32_i32_e32 v92, v92
	v_div_scale_f32 v26, s[0:1], v92, v92, 1.0
	v_rcp_f32_e32 v27, v26
	s_nop 0
	v_fma_f32 v28, -v26, v27, 1.0
	v_fmac_f32_e32 v27, v28, v27
	v_div_scale_f32 v28, vcc, 1.0, v92, 1.0
	v_mul_f32_e32 v29, v28, v27
	v_fma_f32 v30, -v26, v29, v28
	v_fmac_f32_e32 v29, v30, v27
	v_fma_f32 v26, -v26, v29, v28
	s_nop 1
	v_div_fmas_f32 v93, v26, v27, v29
	v_div_fixup_f32 v93, v93, v92, 1.0
	v_fma_f32 v214, v93, v6, -v204
	v_fma_f32 v215, v93, v7, -v205
	v_fma_f32 v216, v93, v8, -v206
	v_fma_f32 v217, v93, v9, -v207
	v_mul_f32_e32 v214, v2, v214
	v_mul_f32_e32 v215, v3, v215
	v_mul_f32_e32 v216, v4, v216
	v_mul_f32_e32 v217, v5, v217
	v_cvt_pk_bf16_f32 v218, v214, v215
	v_cvt_pk_bf16_f32 v219, v216, v217
	global_store_dwordx2 v[24:25], v[218:219], off sc1
	s_waitcnt vmcnt(31)
	v_lshlrev_b32_e32 v200, 16, v106
	v_and_b32_e32 v201, 0xffff0000, v106
	v_lshlrev_b32_e32 v202, 16, v107
	v_and_b32_e32 v203, 0xffff0000, v107
	v_mul_f32_e32 v204, v43, v200
	v_mul_f32_e32 v205, v43, v201
	v_mul_f32_e32 v206, v43, v202
	v_mul_f32_e32 v207, v43, v203
	v_fma_f32 v6, v43, v200, v6
	v_fma_f32 v7, v43, v201, v7
	v_fma_f32 v8, v43, v202, v8
	v_fma_f32 v9, v43, v203, v9
	v_lshlrev_b32_e32 v88, 16, v102
	v_and_b32_e32 v89, 0xffff0000, v102
	v_lshlrev_b32_e32 v90, 16, v103
	v_and_b32_e32 v91, 0xffff0000, v103
	v_mul_f32_e32 v88, v41, v88
	v_mul_f32_e32 v89, v41, v89
	v_mul_f32_e32 v90, v41, v90
	v_mul_f32_e32 v91, v41, v91
	v_sub_f32_e32 v6, v6, v88
	v_sub_f32_e32 v7, v7, v89
	v_sub_f32_e32 v8, v8, v90
	v_sub_f32_e32 v9, v9, v91
	v_fma_f32 v214, v197, v6, -v204
	v_fma_f32 v215, v197, v7, -v205
	v_fma_f32 v216, v197, v8, -v206
	v_fma_f32 v217, v197, v9, -v207
	v_mul_f32_e32 v214, v2, v214
	v_mul_f32_e32 v215, v3, v215
	v_mul_f32_e32 v216, v4, v216
	v_mul_f32_e32 v217, v5, v217
	v_cvt_pk_bf16_f32 v218, v214, v215
	v_cvt_pk_bf16_f32 v219, v216, v217
	global_store_dwordx2 v[24:25], v[218:219], off offset:2048 sc1
	s_mov_b64 s[0:1], 0x1000
	v_lshl_add_u64 v[24:25], v[24:25], 0, s[0:1]
	s_waitcnt vmcnt(31)
	v_lshlrev_b32_e32 v200, 16, v108
	v_and_b32_e32 v201, 0xffff0000, v108
	v_lshlrev_b32_e32 v202, 16, v109
	v_and_b32_e32 v203, 0xffff0000, v109
	v_mul_f32_e32 v204, v44, v200
	v_mul_f32_e32 v205, v44, v201
	v_mul_f32_e32 v206, v44, v202
	v_mul_f32_e32 v207, v44, v203
	v_fma_f32 v6, v44, v200, v6
	v_fma_f32 v7, v44, v201, v7
	v_fma_f32 v8, v44, v202, v8
	v_fma_f32 v9, v44, v203, v9
	v_lshlrev_b32_e32 v88, 16, v104
	v_and_b32_e32 v89, 0xffff0000, v104
	v_lshlrev_b32_e32 v90, 16, v105
	v_and_b32_e32 v91, 0xffff0000, v105
	v_mul_f32_e32 v88, v42, v88
	v_mul_f32_e32 v89, v42, v89
	v_mul_f32_e32 v90, v42, v90
	v_mul_f32_e32 v91, v42, v91
	v_sub_f32_e32 v6, v6, v88
	v_sub_f32_e32 v7, v7, v89
	v_sub_f32_e32 v8, v8, v90
	v_sub_f32_e32 v9, v9, v91
	v_fma_f32 v214, v197, v6, -v204
	v_fma_f32 v215, v197, v7, -v205
	v_fma_f32 v216, v197, v8, -v206
	v_fma_f32 v217, v197, v9, -v207
	v_mul_f32_e32 v214, v2, v214
	v_mul_f32_e32 v215, v3, v215
	v_mul_f32_e32 v216, v4, v216
	v_mul_f32_e32 v217, v5, v217
	v_cvt_pk_bf16_f32 v218, v214, v215
	v_cvt_pk_bf16_f32 v219, v216, v217
	global_store_dwordx2 v[24:25], v[218:219], off sc1
	s_waitcnt vmcnt(31)
	v_lshlrev_b32_e32 v200, 16, v110
	v_and_b32_e32 v201, 0xffff0000, v110
	v_lshlrev_b32_e32 v202, 16, v111
	v_and_b32_e32 v203, 0xffff0000, v111
	v_mul_f32_e32 v204, v45, v200
	v_mul_f32_e32 v205, v45, v201
	v_mul_f32_e32 v206, v45, v202
	v_mul_f32_e32 v207, v45, v203
	v_fma_f32 v6, v45, v200, v6
	v_fma_f32 v7, v45, v201, v7
	v_fma_f32 v8, v45, v202, v8
	v_fma_f32 v9, v45, v203, v9
	v_lshlrev_b32_e32 v88, 16, v106
	v_and_b32_e32 v89, 0xffff0000, v106
	v_lshlrev_b32_e32 v90, 16, v107
	v_and_b32_e32 v91, 0xffff0000, v107
	v_mul_f32_e32 v88, v43, v88
	v_mul_f32_e32 v89, v43, v89
	v_mul_f32_e32 v90, v43, v90
	v_mul_f32_e32 v91, v43, v91
	v_sub_f32_e32 v6, v6, v88
	v_sub_f32_e32 v7, v7, v89
	v_sub_f32_e32 v8, v8, v90
	v_sub_f32_e32 v9, v9, v91
	v_fma_f32 v214, v197, v6, -v204
	v_fma_f32 v215, v197, v7, -v205
	v_fma_f32 v216, v197, v8, -v206
	v_fma_f32 v217, v197, v9, -v207
	v_mul_f32_e32 v214, v2, v214
	v_mul_f32_e32 v215, v3, v215
	v_mul_f32_e32 v216, v4, v216
	v_mul_f32_e32 v217, v5, v217
	v_cvt_pk_bf16_f32 v218, v214, v215
	v_cvt_pk_bf16_f32 v219, v216, v217
	global_store_dwordx2 v[24:25], v[218:219], off offset:2048 sc1
	s_mov_b64 s[0:1], 0x1000
	v_lshl_add_u64 v[24:25], v[24:25], 0, s[0:1]
	s_waitcnt vmcnt(31)
; __device__ __forceinline__ unsigned pk2(float lo, float hi) { return pg8::cvt_pk_bf16(lo, hi); }
; __device__ __forceinline__ f32x4 ld4bf(const bf16* p) { const v2u w = *(const v2u*)p; return (f32x4){bf_lo(w.x), bf_hi(w.x), bf_lo(w.y), bf_hi(w.y)}; }
; __device__ __forceinline__ void pool_prep(const bf16* X, const float* ss, const float* gain, bf16* PB, LAS unsigned char* lds, int vcu, int G, int tid) {
;     ...
;         for (int i = 0; i < 32; ++i) { const int row = ra + i, t = row - bstart;
;             const f32x4 xn = ld4bf(xp + (size_t)row * DM) * rsl[row - r0 + 16];
;             f32x4 old = {0.f, 0.f, 0.f, 0.f};
;             if (t >= w) old = ld4bf(xp + (size_t)(row - w) * DM) * rsl[row - w - r0 + 16];
;             S = S + xn - old;
;             const int cnt = (t + 1 < w) ? t + 1 : w;
;             const f32x4 p = (S * (1.0f / (float)cnt) - xn) * gn;
;             v2u o; o.x = pk2(p[0], p[1]); o.y = pk2(p[2], p[3]); *(v2u*)(PB + (size_t)row * DM + 4 * q) = o; }
	v_lshlrev_b32_e32 v200, 16, v112
	v_and_b32_e32 v201, 0xffff0000, v112
	v_lshlrev_b32_e32 v202, 16, v113
	v_and_b32_e32 v203, 0xffff0000, v113
	v_mul_f32_e32 v204, v46, v200
	v_mul_f32_e32 v205, v46, v201
	v_mul_f32_e32 v206, v46, v202
	v_mul_f32_e32 v207, v46, v203
	v_fma_f32 v6, v46, v200, v6
	v_fma_f32 v7, v46, v201, v7
	v_fma_f32 v8, v46, v202, v8
	v_fma_f32 v9, v46, v203, v9
	v_lshlrev_b32_e32 v88, 16, v108
	v_and_b32_e32 v89, 0xffff0000, v108
	v_lshlrev_b32_e32 v90, 16, v109
	v_and_b32_e32 v91, 0xffff0000, v109
	v_mul_f32_e32 v88, v44, v88
	v_mul_f32_e32 v89, v44, v89
	v_mul_f32_e32 v90, v44, v90
	v_mul_f32_e32 v91, v44, v91
	v_sub_f32_e32 v6, v6, v88
	v_sub_f32_e32 v7, v7, v89
	v_sub_f32_e32 v8, v8, v90
	v_sub_f32_e32 v9, v9, v91
	v_fma_f32 v214, v197, v6, -v204
	v_fma_f32 v215, v197, v7, -v205
	v_fma_f32 v216, v197, v8, -v206
	v_fma_f32 v217, v197, v9, -v207
	v_mul_f32_e32 v214, v2, v214
	v_mul_f32_e32 v215, v3, v215
	v_mul_f32_e32 v216, v4, v216
	v_mul_f32_e32 v217, v5, v217
	v_cvt_pk_bf16_f32 v218, v214, v215
	v_cvt_pk_bf16_f32 v219, v216, v217
	global_store_dwordx2 v[24:25], v[218:219], off sc1
	s_waitcnt vmcnt(31)
	v_lshlrev_b32_e32 v200, 16, v114
	v_and_b32_e32 v201, 0xffff0000, v114
	v_lshlrev_b32_e32 v202, 16, v115
	v_and_b32_e32 v203, 0xffff0000, v115
	v_mul_f32_e32 v204, v47, v200
	v_mul_f32_e32 v205, v47, v201
	v_mul_f32_e32 v206, v47, v202
	v_mul_f32_e32 v207, v47, v203
	v_fma_f32 v6, v47, v200, v6
	v_fma_f32 v7, v47, v201, v7
	v_fma_f32 v8, v47, v202, v8
	v_fma_f32 v9, v47, v203, v9
	v_lshlrev_b32_e32 v88, 16, v110
	v_and_b32_e32 v89, 0xffff0000, v110
	v_lshlrev_b32_e32 v90, 16, v111
	v_and_b32_e32 v91, 0xffff0000, v111
	v_mul_f32_e32 v88, v45, v88
	v_mul_f32_e32 v89, v45, v89
	v_mul_f32_e32 v90, v45, v90
	v_mul_f32_e32 v91, v45, v91
	v_sub_f32_e32 v6, v6, v88
	v_sub_f32_e32 v7, v7, v89
	v_sub_f32_e32 v8, v8, v90
	v_sub_f32_e32 v9, v9, v91
	v_fma_f32 v214, v197, v6, -v204
	v_fma_f32 v215, v197, v7, -v205
	v_fma_f32 v216, v197, v8, -v206
	v_fma_f32 v217, v197, v9, -v207
	v_mul_f32_e32 v214, v2, v214
	v_mul_f32_e32 v215, v3, v215
	v_mul_f32_e32 v216, v4, v216
	v_mul_f32_e32 v217, v5, v217
	v_cvt_pk_bf16_f32 v218, v214, v215
	v_cvt_pk_bf16_f32 v219, v216, v217
	global_store_dwordx2 v[24:25], v[218:219], off offset:2048 sc1
	s_mov_b64 s[0:1], 0x1000
	v_lshl_add_u64 v[24:25], v[24:25], 0, s[0:1]
	s_waitcnt vmcnt(31)
	v_lshlrev_b32_e32 v200, 16, v116
	v_and_b32_e32 v201, 0xffff0000, v116
	v_lshlrev_b32_e32 v202, 16, v117
	v_and_b32_e32 v203, 0xffff0000, v117
	v_mul_f32_e32 v204, v48, v200
	v_mul_f32_e32 v205, v48, v201
	v_mul_f32_e32 v206, v48, v202
	v_mul_f32_e32 v207, v48, v203
	v_fma_f32 v6, v48, v200, v6
	v_fma_f32 v7, v48, v201, v7
	v_fma_f32 v8, v48, v202, v8
	v_fma_f32 v9, v48, v203, v9
	v_lshlrev_b32_e32 v88, 16, v112
	v_and_b32_e32 v89, 0xffff0000, v112
	v_lshlrev_b32_e32 v90, 16, v113
	v_and_b32_e32 v91, 0xffff0000, v113
	v_mul_f32_e32 v88, v46, v88
	v_mul_f32_e32 v89, v46, v89
	v_mul_f32_e32 v90, v46, v90
	v_mul_f32_e32 v91, v46, v91
	v_sub_f32_e32 v6, v6, v88
	v_sub_f32_e32 v7, v7, v89
	v_sub_f32_e32 v8, v8, v90
	v_sub_f32_e32 v9, v9, v91
	v_fma_f32 v214, v197, v6, -v204
	v_fma_f32 v215, v197, v7, -v205
	v_fma_f32 v216, v197, v8, -v206
	v_fma_f32 v217, v197, v9, -v207
	v_mul_f32_e32 v214, v2, v214
	v_mul_f32_e32 v215, v3, v215
	v_mul_f32_e32 v216, v4, v216
	v_mul_f32_e32 v217, v5, v217
	v_cvt_pk_bf16_f32 v218, v214, v215
	v_cvt_pk_bf16_f32 v219, v216, v217
	global_store_dwordx2 v[24:25], v[218:219], off sc1
	s_waitcnt vmcnt(31)
	v_lshlrev_b32_e32 v200, 16, v118
	v_and_b32_e32 v201, 0xffff0000, v118
	v_lshlrev_b32_e32 v202, 16, v119
	v_and_b32_e32 v203, 0xffff0000, v119
	v_mul_f32_e32 v204, v49, v200
	v_mul_f32_e32 v205, v49, v201
	v_mul_f32_e32 v206, v49, v202
	v_mul_f32_e32 v207, v49, v203
	v_fma_f32 v6, v49, v200, v6
	v_fma_f32 v7, v49, v201, v7
	v_fma_f32 v8, v49, v202, v8
	v_fma_f32 v9, v49, v203, v9
	v_lshlrev_b32_e32 v88, 16, v114
	v_and_b32_e32 v89, 0xffff0000, v114
	v_lshlrev_b32_e32 v90, 16, v115
	v_and_b32_e32 v91, 0xffff0000, v115
	v_mul_f32_e32 v88, v47, v88
	v_mul_f32_e32 v89, v47, v89
	v_mul_f32_e32 v90, v47, v90
	v_mul_f32_e32 v91, v47, v91
	v_sub_f32_e32 v6, v6, v88
	v_sub_f32_e32 v7, v7, v89
	v_sub_f32_e32 v8, v8, v90
	v_sub_f32_e32 v9, v9, v91
	v_fma_f32 v214, v197, v6, -v204
	v_fma_f32 v215, v197, v7, -v205
	v_fma_f32 v216, v197, v8, -v206
	v_fma_f32 v217, v197, v9, -v207
	v_mul_f32_e32 v214, v2, v214
	v_mul_f32_e32 v215, v3, v215
	v_mul_f32_e32 v216, v4, v216
	v_mul_f32_e32 v217, v5, v217
	v_cvt_pk_bf16_f32 v218, v214, v215
	v_cvt_pk_bf16_f32 v219, v216, v217
	global_store_dwordx2 v[24:25], v[218:219], off offset:2048 sc1
	s_mov_b64 s[0:1], 0x1000
	v_lshl_add_u64 v[24:25], v[24:25], 0, s[0:1]
	s_waitcnt vmcnt(31)
	v_lshlrev_b32_e32 v200, 16, v120
	v_and_b32_e32 v201, 0xffff0000, v120
	v_lshlrev_b32_e32 v202, 16, v121
	v_and_b32_e32 v203, 0xffff0000, v121
	v_mul_f32_e32 v204, v50, v200
	v_mul_f32_e32 v205, v50, v201
	v_mul_f32_e32 v206, v50, v202
	v_mul_f32_e32 v207, v50, v203
	v_fma_f32 v6, v50, v200, v6
	v_fma_f32 v7, v50, v201, v7
	v_fma_f32 v8, v50, v202, v8
	v_fma_f32 v9, v50, v203, v9
	v_lshlrev_b32_e32 v88, 16, v116
	v_and_b32_e32 v89, 0xffff0000, v116
	v_lshlrev_b32_e32 v90, 16, v117
	v_and_b32_e32 v91, 0xffff0000, v117
	v_mul_f32_e32 v88, v48, v88
	v_mul_f32_e32 v89, v48, v89
	v_mul_f32_e32 v90, v48, v90
	v_mul_f32_e32 v91, v48, v91
	v_sub_f32_e32 v6, v6, v88
	v_sub_f32_e32 v7, v7, v89
	v_sub_f32_e32 v8, v8, v90
	v_sub_f32_e32 v9, v9, v91
	v_fma_f32 v214, v197, v6, -v204
	v_fma_f32 v215, v197, v7, -v205
	v_fma_f32 v216, v197, v8, -v206
	v_fma_f32 v217, v197, v9, -v207
	v_mul_f32_e32 v214, v2, v214
	v_mul_f32_e32 v215, v3, v215
	v_mul_f32_e32 v216, v4, v216
	v_mul_f32_e32 v217, v5, v217
	v_cvt_pk_bf16_f32 v218, v214, v215
	v_cvt_pk_bf16_f32 v219, v216, v217
	global_store_dwordx2 v[24:25], v[218:219], off sc1
	s_waitcnt vmcnt(31)
; __device__ __forceinline__ unsigned pk2(float lo, float hi) { return pg8::cvt_pk_bf16(lo, hi); }
; __device__ __forceinline__ f32x4 ld4bf(const bf16* p) { const v2u w = *(const v2u*)p; return (f32x4){bf_lo(w.x), bf_hi(w.x), bf_lo(w.y), bf_hi(w.y)}; }
; __device__ __forceinline__ void pool_prep(const bf16* X, const float* ss, const float* gain, bf16* PB, LAS unsigned char* lds, int vcu, int G, int tid) {
;     ...
;         for (int i = 0; i < 32; ++i) { const int row = ra + i, t = row - bstart;
;             const f32x4 xn = ld4bf(xp + (size_t)row * DM) * rsl[row - r0 + 16];
;             f32x4 old = {0.f, 0.f, 0.f, 0.f};
;             if (t >= w) old = ld4bf(xp + (size_t)(row - w) * DM) * rsl[row - w - r0 + 16];
;             S = S + xn - old;
;             const int cnt = (t + 1 < w) ? t + 1 : w;
;             const f32x4 p = (S * (1.0f / (float)cnt) - xn) * gn;
;             v2u o; o.x = pk2(p[0], p[1]); o.y = pk2(p[2], p[3]); *(v2u*)(PB + (size_t)row * DM + 4 * q) = o; }
	v_lshlrev_b32_e32 v200, 16, v122
	v_and_b32_e32 v201, 0xffff0000, v122
	v_lshlrev_b32_e32 v202, 16, v123
	v_and_b32_e32 v203, 0xffff0000, v123
	v_mul_f32_e32 v204, v51, v200
	v_mul_f32_e32 v205, v51, v201
	v_mul_f32_e32 v206, v51, v202
	v_mul_f32_e32 v207, v51, v203
	v_fma_f32 v6, v51, v200, v6
	v_fma_f32 v7, v51, v201, v7
	v_fma_f32 v8, v51, v202, v8
	v_fma_f32 v9, v51, v203, v9
	v_lshlrev_b32_e32 v88, 16, v118
	v_and_b32_e32 v89, 0xffff0000, v118
	v_lshlrev_b32_e32 v90, 16, v119
	v_and_b32_e32 v91, 0xffff0000, v119
	v_mul_f32_e32 v88, v49, v88
	v_mul_f32_e32 v89, v49, v89
	v_mul_f32_e32 v90, v49, v90
	v_mul_f32_e32 v91, v49, v91
	v_sub_f32_e32 v6, v6, v88
	v_sub_f32_e32 v7, v7, v89
	v_sub_f32_e32 v8, v8, v90
	v_sub_f32_e32 v9, v9, v91
	v_fma_f32 v214, v197, v6, -v204
	v_fma_f32 v215, v197, v7, -v205
	v_fma_f32 v216, v197, v8, -v206
	v_fma_f32 v217, v197, v9, -v207
	v_mul_f32_e32 v214, v2, v214
	v_mul_f32_e32 v215, v3, v215
	v_mul_f32_e32 v216, v4, v216
	v_mul_f32_e32 v217, v5, v217
	v_cvt_pk_bf16_f32 v218, v214, v215
	v_cvt_pk_bf16_f32 v219, v216, v217
	global_store_dwordx2 v[24:25], v[218:219], off offset:2048 sc1
	s_mov_b64 s[0:1], 0x1000
	v_lshl_add_u64 v[24:25], v[24:25], 0, s[0:1]
	s_waitcnt vmcnt(31)
	v_lshlrev_b32_e32 v200, 16, v124
	v_and_b32_e32 v201, 0xffff0000, v124
	v_lshlrev_b32_e32 v202, 16, v125
	v_and_b32_e32 v203, 0xffff0000, v125
	v_mul_f32_e32 v204, v52, v200
	v_mul_f32_e32 v205, v52, v201
	v_mul_f32_e32 v206, v52, v202
	v_mul_f32_e32 v207, v52, v203
	v_fma_f32 v6, v52, v200, v6
	v_fma_f32 v7, v52, v201, v7
	v_fma_f32 v8, v52, v202, v8
	v_fma_f32 v9, v52, v203, v9
	v_lshlrev_b32_e32 v88, 16, v120
	v_and_b32_e32 v89, 0xffff0000, v120
	v_lshlrev_b32_e32 v90, 16, v121
	v_and_b32_e32 v91, 0xffff0000, v121
	v_mul_f32_e32 v88, v50, v88
	v_mul_f32_e32 v89, v50, v89
	v_mul_f32_e32 v90, v50, v90
	v_mul_f32_e32 v91, v50, v91
	v_sub_f32_e32 v6, v6, v88
	v_sub_f32_e32 v7, v7, v89
	v_sub_f32_e32 v8, v8, v90
	v_sub_f32_e32 v9, v9, v91
	v_fma_f32 v214, v197, v6, -v204
	v_fma_f32 v215, v197, v7, -v205
	v_fma_f32 v216, v197, v8, -v206
	v_fma_f32 v217, v197, v9, -v207
	v_mul_f32_e32 v214, v2, v214
	v_mul_f32_e32 v215, v3, v215
	v_mul_f32_e32 v216, v4, v216
	v_mul_f32_e32 v217, v5, v217
	v_cvt_pk_bf16_f32 v218, v214, v215
	v_cvt_pk_bf16_f32 v219, v216, v217
	global_store_dwordx2 v[24:25], v[218:219], off sc1
	s_waitcnt vmcnt(31)
	v_lshlrev_b32_e32 v200, 16, v126
	v_and_b32_e32 v201, 0xffff0000, v126
	v_lshlrev_b32_e32 v202, 16, v127
	v_and_b32_e32 v203, 0xffff0000, v127
	v_mul_f32_e32 v204, v53, v200
	v_mul_f32_e32 v205, v53, v201
	v_mul_f32_e32 v206, v53, v202
	v_mul_f32_e32 v207, v53, v203
	v_fma_f32 v6, v53, v200, v6
	v_fma_f32 v7, v53, v201, v7
	v_fma_f32 v8, v53, v202, v8
	v_fma_f32 v9, v53, v203, v9
	v_lshlrev_b32_e32 v88, 16, v122
	v_and_b32_e32 v89, 0xffff0000, v122
	v_lshlrev_b32_e32 v90, 16, v123
	v_and_b32_e32 v91, 0xffff0000, v123
	v_mul_f32_e32 v88, v51, v88
	v_mul_f32_e32 v89, v51, v89
	v_mul_f32_e32 v90, v51, v90
	v_mul_f32_e32 v91, v51, v91
	v_sub_f32_e32 v6, v6, v88
	v_sub_f32_e32 v7, v7, v89
	v_sub_f32_e32 v8, v8, v90
	v_sub_f32_e32 v9, v9, v91
	v_fma_f32 v214, v197, v6, -v204
	v_fma_f32 v215, v197, v7, -v205
	v_fma_f32 v216, v197, v8, -v206
	v_fma_f32 v217, v197, v9, -v207
	v_mul_f32_e32 v214, v2, v214
	v_mul_f32_e32 v215, v3, v215
	v_mul_f32_e32 v216, v4, v216
	v_mul_f32_e32 v217, v5, v217
	v_cvt_pk_bf16_f32 v218, v214, v215
	v_cvt_pk_bf16_f32 v219, v216, v217
	global_store_dwordx2 v[24:25], v[218:219], off offset:2048 sc1
	s_mov_b64 s[0:1], 0x1000
	v_lshl_add_u64 v[24:25], v[24:25], 0, s[0:1]
	s_waitcnt vmcnt(31)
	v_lshlrev_b32_e32 v200, 16, v128
	v_and_b32_e32 v201, 0xffff0000, v128
	v_lshlrev_b32_e32 v202, 16, v129
	v_and_b32_e32 v203, 0xffff0000, v129
	v_mul_f32_e32 v204, v54, v200
	v_mul_f32_e32 v205, v54, v201
	v_mul_f32_e32 v206, v54, v202
	v_mul_f32_e32 v207, v54, v203
	v_fma_f32 v6, v54, v200, v6
	v_fma_f32 v7, v54, v201, v7
	v_fma_f32 v8, v54, v202, v8
	v_fma_f32 v9, v54, v203, v9
	v_lshlrev_b32_e32 v88, 16, v124
	v_and_b32_e32 v89, 0xffff0000, v124
	v_lshlrev_b32_e32 v90, 16, v125
	v_and_b32_e32 v91, 0xffff0000, v125
	v_mul_f32_e32 v88, v52, v88
	v_mul_f32_e32 v89, v52, v89
	v_mul_f32_e32 v90, v52, v90
	v_mul_f32_e32 v91, v52, v91
	v_sub_f32_e32 v6, v6, v88
	v_sub_f32_e32 v7, v7, v89
	v_sub_f32_e32 v8, v8, v90
	v_sub_f32_e32 v9, v9, v91
	v_fma_f32 v214, v197, v6, -v204
	v_fma_f32 v215, v197, v7, -v205
	v_fma_f32 v216, v197, v8, -v206
	v_fma_f32 v217, v197, v9, -v207
	v_mul_f32_e32 v214, v2, v214
	v_mul_f32_e32 v215, v3, v215
	v_mul_f32_e32 v216, v4, v216
	v_mul_f32_e32 v217, v5, v217
	v_cvt_pk_bf16_f32 v218, v214, v215
	v_cvt_pk_bf16_f32 v219, v216, v217
	global_store_dwordx2 v[24:25], v[218:219], off sc1
	s_waitcnt vmcnt(31)
	v_lshlrev_b32_e32 v200, 16, v130
	v_and_b32_e32 v201, 0xffff0000, v130
	v_lshlrev_b32_e32 v202, 16, v131
	v_and_b32_e32 v203, 0xffff0000, v131
	v_mul_f32_e32 v204, v55, v200
	v_mul_f32_e32 v205, v55, v201
	v_mul_f32_e32 v206, v55, v202
	v_mul_f32_e32 v207, v55, v203
	v_fma_f32 v6, v55, v200, v6
	v_fma_f32 v7, v55, v201, v7
	v_fma_f32 v8, v55, v202, v8
	v_fma_f32 v9, v55, v203, v9
	v_lshlrev_b32_e32 v88, 16, v126
	v_and_b32_e32 v89, 0xffff0000, v126
	v_lshlrev_b32_e32 v90, 16, v127
	v_and_b32_e32 v91, 0xffff0000, v127
	v_mul_f32_e32 v88, v53, v88
	v_mul_f32_e32 v89, v53, v89
	v_mul_f32_e32 v90, v53, v90
	v_mul_f32_e32 v91, v53, v91
	v_sub_f32_e32 v6, v6, v88
	v_sub_f32_e32 v7, v7, v89
	v_sub_f32_e32 v8, v8, v90
	v_sub_f32_e32 v9, v9, v91
	v_fma_f32 v214, v197, v6, -v204
	v_fma_f32 v215, v197, v7, -v205
	v_fma_f32 v216, v197, v8, -v206
	v_fma_f32 v217, v197, v9, -v207
	v_mul_f32_e32 v214, v2, v214
	v_mul_f32_e32 v215, v3, v215
	v_mul_f32_e32 v216, v4, v216
	v_mul_f32_e32 v217, v5, v217
	v_cvt_pk_bf16_f32 v218, v214, v215
	v_cvt_pk_bf16_f32 v219, v216, v217
	global_store_dwordx2 v[24:25], v[218:219], off offset:2048 sc1
	s_mov_b64 s[0:1], 0x1000
	v_lshl_add_u64 v[24:25], v[24:25], 0, s[0:1]
	s_waitcnt vmcnt(31)
; __device__ __forceinline__ unsigned pk2(float lo, float hi) { return pg8::cvt_pk_bf16(lo, hi); }
; __device__ __forceinline__ f32x4 ld4bf(const bf16* p) { const v2u w = *(const v2u*)p; return (f32x4){bf_lo(w.x), bf_hi(w.x), bf_lo(w.y), bf_hi(w.y)}; }
; __device__ __forceinline__ void pool_prep(const bf16* X, const float* ss, const float* gain, bf16* PB, LAS unsigned char* lds, int vcu, int G, int tid) {
;     ...
;         for (int i = 0; i < 32; ++i) { const int row = ra + i, t = row - bstart;
;             const f32x4 xn = ld4bf(xp + (size_t)row * DM) * rsl[row - r0 + 16];
;             f32x4 old = {0.f, 0.f, 0.f, 0.f};
;             if (t >= w) old = ld4bf(xp + (size_t)(row - w) * DM) * rsl[row - w - r0 + 16];
;             S = S + xn - old;
;             const int cnt = (t + 1 < w) ? t + 1 : w;
;             const f32x4 p = (S * (1.0f / (float)cnt) - xn) * gn;
;             v2u o; o.x = pk2(p[0], p[1]); o.y = pk2(p[2], p[3]); *(v2u*)(PB + (size_t)row * DM + 4 * q) = o; }
	v_lshlrev_b32_e32 v200, 16, v132
	v_and_b32_e32 v201, 0xffff0000, v132
	v_lshlrev_b32_e32 v202, 16, v133
	v_and_b32_e32 v203, 0xffff0000, v133
	v_mul_f32_e32 v204, v56, v200
	v_mul_f32_e32 v205, v56, v201
	v_mul_f32_e32 v206, v56, v202
	v_mul_f32_e32 v207, v56, v203
	v_fma_f32 v6, v56, v200, v6
	v_fma_f32 v7, v56, v201, v7
	v_fma_f32 v8, v56, v202, v8
	v_fma_f32 v9, v56, v203, v9
	v_lshlrev_b32_e32 v88, 16, v128
	v_and_b32_e32 v89, 0xffff0000, v128
	v_lshlrev_b32_e32 v90, 16, v129
	v_and_b32_e32 v91, 0xffff0000, v129
	v_mul_f32_e32 v88, v54, v88
	v_mul_f32_e32 v89, v54, v89
	v_mul_f32_e32 v90, v54, v90
	v_mul_f32_e32 v91, v54, v91
	v_sub_f32_e32 v6, v6, v88
	v_sub_f32_e32 v7, v7, v89
	v_sub_f32_e32 v8, v8, v90
	v_sub_f32_e32 v9, v9, v91
	v_fma_f32 v214, v197, v6, -v204
	v_fma_f32 v215, v197, v7, -v205
	v_fma_f32 v216, v197, v8, -v206
	v_fma_f32 v217, v197, v9, -v207
	v_mul_f32_e32 v214, v2, v214
	v_mul_f32_e32 v215, v3, v215
	v_mul_f32_e32 v216, v4, v216
	v_mul_f32_e32 v217, v5, v217
	v_cvt_pk_bf16_f32 v218, v214, v215
	v_cvt_pk_bf16_f32 v219, v216, v217
	global_store_dwordx2 v[24:25], v[218:219], off sc1
	s_waitcnt vmcnt(31)
	v_lshlrev_b32_e32 v200, 16, v134
	v_and_b32_e32 v201, 0xffff0000, v134
	v_lshlrev_b32_e32 v202, 16, v135
	v_and_b32_e32 v203, 0xffff0000, v135
	v_mul_f32_e32 v204, v57, v200
	v_mul_f32_e32 v205, v57, v201
	v_mul_f32_e32 v206, v57, v202
	v_mul_f32_e32 v207, v57, v203
	v_fma_f32 v6, v57, v200, v6
	v_fma_f32 v7, v57, v201, v7
	v_fma_f32 v8, v57, v202, v8
	v_fma_f32 v9, v57, v203, v9
	v_lshlrev_b32_e32 v88, 16, v130
	v_and_b32_e32 v89, 0xffff0000, v130
	v_lshlrev_b32_e32 v90, 16, v131
	v_and_b32_e32 v91, 0xffff0000, v131
	v_mul_f32_e32 v88, v55, v88
	v_mul_f32_e32 v89, v55, v89
	v_mul_f32_e32 v90, v55, v90
	v_mul_f32_e32 v91, v55, v91
	v_sub_f32_e32 v6, v6, v88
	v_sub_f32_e32 v7, v7, v89
	v_sub_f32_e32 v8, v8, v90
	v_sub_f32_e32 v9, v9, v91
	v_fma_f32 v214, v197, v6, -v204
	v_fma_f32 v215, v197, v7, -v205
	v_fma_f32 v216, v197, v8, -v206
	v_fma_f32 v217, v197, v9, -v207
	v_mul_f32_e32 v214, v2, v214
	v_mul_f32_e32 v215, v3, v215
	v_mul_f32_e32 v216, v4, v216
	v_mul_f32_e32 v217, v5, v217
	v_cvt_pk_bf16_f32 v218, v214, v215
	v_cvt_pk_bf16_f32 v219, v216, v217
	global_store_dwordx2 v[24:25], v[218:219], off offset:2048 sc1
	s_mov_b64 s[0:1], 0x1000
	v_lshl_add_u64 v[24:25], v[24:25], 0, s[0:1]
	s_waitcnt vmcnt(31)
	v_lshlrev_b32_e32 v200, 16, v136
	v_and_b32_e32 v201, 0xffff0000, v136
	v_lshlrev_b32_e32 v202, 16, v137
	v_and_b32_e32 v203, 0xffff0000, v137
	v_mul_f32_e32 v204, v58, v200
	v_mul_f32_e32 v205, v58, v201
	v_mul_f32_e32 v206, v58, v202
	v_mul_f32_e32 v207, v58, v203
	v_fma_f32 v6, v58, v200, v6
	v_fma_f32 v7, v58, v201, v7
	v_fma_f32 v8, v58, v202, v8
	v_fma_f32 v9, v58, v203, v9
	v_lshlrev_b32_e32 v88, 16, v132
	v_and_b32_e32 v89, 0xffff0000, v132
	v_lshlrev_b32_e32 v90, 16, v133
	v_and_b32_e32 v91, 0xffff0000, v133
	v_mul_f32_e32 v88, v56, v88
	v_mul_f32_e32 v89, v56, v89
	v_mul_f32_e32 v90, v56, v90
	v_mul_f32_e32 v91, v56, v91
	v_sub_f32_e32 v6, v6, v88
	v_sub_f32_e32 v7, v7, v89
	v_sub_f32_e32 v8, v8, v90
	v_sub_f32_e32 v9, v9, v91
	v_fma_f32 v214, v197, v6, -v204
	v_fma_f32 v215, v197, v7, -v205
	v_fma_f32 v216, v197, v8, -v206
	v_fma_f32 v217, v197, v9, -v207
	v_mul_f32_e32 v214, v2, v214
	v_mul_f32_e32 v215, v3, v215
	v_mul_f32_e32 v216, v4, v216
	v_mul_f32_e32 v217, v5, v217
	v_cvt_pk_bf16_f32 v218, v214, v215
	v_cvt_pk_bf16_f32 v219, v216, v217
	global_store_dwordx2 v[24:25], v[218:219], off sc1
	s_waitcnt vmcnt(31)
	v_lshlrev_b32_e32 v200, 16, v138
	v_and_b32_e32 v201, 0xffff0000, v138
	v_lshlrev_b32_e32 v202, 16, v139
	v_and_b32_e32 v203, 0xffff0000, v139
	v_mul_f32_e32 v204, v59, v200
	v_mul_f32_e32 v205, v59, v201
	v_mul_f32_e32 v206, v59, v202
	v_mul_f32_e32 v207, v59, v203
	v_fma_f32 v6, v59, v200, v6
	v_fma_f32 v7, v59, v201, v7
	v_fma_f32 v8, v59, v202, v8
	v_fma_f32 v9, v59, v203, v9
	v_lshlrev_b32_e32 v88, 16, v134
	v_and_b32_e32 v89, 0xffff0000, v134
	v_lshlrev_b32_e32 v90, 16, v135
	v_and_b32_e32 v91, 0xffff0000, v135
	v_mul_f32_e32 v88, v57, v88
	v_mul_f32_e32 v89, v57, v89
	v_mul_f32_e32 v90, v57, v90
	v_mul_f32_e32 v91, v57, v91
	v_sub_f32_e32 v6, v6, v88
	v_sub_f32_e32 v7, v7, v89
	v_sub_f32_e32 v8, v8, v90
	v_sub_f32_e32 v9, v9, v91
	v_fma_f32 v214, v197, v6, -v204
	v_fma_f32 v215, v197, v7, -v205
	v_fma_f32 v216, v197, v8, -v206
	v_fma_f32 v217, v197, v9, -v207
	v_mul_f32_e32 v214, v2, v214
	v_mul_f32_e32 v215, v3, v215
	v_mul_f32_e32 v216, v4, v216
	v_mul_f32_e32 v217, v5, v217
	v_cvt_pk_bf16_f32 v218, v214, v215
	v_cvt_pk_bf16_f32 v219, v216, v217
	global_store_dwordx2 v[24:25], v[218:219], off offset:2048 sc1
	s_mov_b64 s[0:1], 0x1000
	v_lshl_add_u64 v[24:25], v[24:25], 0, s[0:1]
	s_waitcnt vmcnt(31)
	v_lshlrev_b32_e32 v200, 16, v140
	v_and_b32_e32 v201, 0xffff0000, v140
	v_lshlrev_b32_e32 v202, 16, v141
	v_and_b32_e32 v203, 0xffff0000, v141
	v_mul_f32_e32 v204, v60, v200
	v_mul_f32_e32 v205, v60, v201
	v_mul_f32_e32 v206, v60, v202
	v_mul_f32_e32 v207, v60, v203
	v_fma_f32 v6, v60, v200, v6
	v_fma_f32 v7, v60, v201, v7
	v_fma_f32 v8, v60, v202, v8
	v_fma_f32 v9, v60, v203, v9
	v_lshlrev_b32_e32 v88, 16, v136
	v_and_b32_e32 v89, 0xffff0000, v136
	v_lshlrev_b32_e32 v90, 16, v137
	v_and_b32_e32 v91, 0xffff0000, v137
	v_mul_f32_e32 v88, v58, v88
	v_mul_f32_e32 v89, v58, v89
	v_mul_f32_e32 v90, v58, v90
	v_mul_f32_e32 v91, v58, v91
	v_sub_f32_e32 v6, v6, v88
	v_sub_f32_e32 v7, v7, v89
	v_sub_f32_e32 v8, v8, v90
	v_sub_f32_e32 v9, v9, v91
	v_fma_f32 v214, v197, v6, -v204
	v_fma_f32 v215, v197, v7, -v205
	v_fma_f32 v216, v197, v8, -v206
	v_fma_f32 v217, v197, v9, -v207
	v_mul_f32_e32 v214, v2, v214
	v_mul_f32_e32 v215, v3, v215
	v_mul_f32_e32 v216, v4, v216
	v_mul_f32_e32 v217, v5, v217
	v_cvt_pk_bf16_f32 v218, v214, v215
	v_cvt_pk_bf16_f32 v219, v216, v217
	global_store_dwordx2 v[24:25], v[218:219], off sc1
	s_waitcnt vmcnt(31)
; __device__ __forceinline__ unsigned pk2(float lo, float hi) { return pg8::cvt_pk_bf16(lo, hi); }
; __device__ __forceinline__ f32x4 ld4bf(const bf16* p) { const v2u w = *(const v2u*)p; return (f32x4){bf_lo(w.x), bf_hi(w.x), bf_lo(w.y), bf_hi(w.y)}; }
; __device__ __forceinline__ void pool_prep(const bf16* X, const float* ss, const float* gain, bf16* PB, LAS unsigned char* lds, int vcu, int G, int tid) {
;     ...
;         for (int i = 0; i < 32; ++i) { const int row = ra + i, t = row - bstart;
;             const f32x4 xn = ld4bf(xp + (size_t)row * DM) * rsl[row - r0 + 16];
;             f32x4 old = {0.f, 0.f, 0.f, 0.f};
;             if (t >= w) old = ld4bf(xp + (size_t)(row - w) * DM) * rsl[row - w - r0 + 16];
;             S = S + xn - old;
;             const int cnt = (t + 1 < w) ? t + 1 : w;
;             const f32x4 p = (S * (1.0f / (float)cnt) - xn) * gn;
;             v2u o; o.x = pk2(p[0], p[1]); o.y = pk2(p[2], p[3]); *(v2u*)(PB + (size_t)row * DM + 4 * q) = o; }
	v_lshlrev_b32_e32 v200, 16, v142
	v_and_b32_e32 v201, 0xffff0000, v142
	v_lshlrev_b32_e32 v202, 16, v143
	v_and_b32_e32 v203, 0xffff0000, v143
	v_mul_f32_e32 v204, v61, v200
	v_mul_f32_e32 v205, v61, v201
	v_mul_f32_e32 v206, v61, v202
	v_mul_f32_e32 v207, v61, v203
	v_fma_f32 v6, v61, v200, v6
	v_fma_f32 v7, v61, v201, v7
	v_fma_f32 v8, v61, v202, v8
	v_fma_f32 v9, v61, v203, v9
	v_lshlrev_b32_e32 v88, 16, v138
	v_and_b32_e32 v89, 0xffff0000, v138
	v_lshlrev_b32_e32 v90, 16, v139
	v_and_b32_e32 v91, 0xffff0000, v139
	v_mul_f32_e32 v88, v59, v88
	v_mul_f32_e32 v89, v59, v89
	v_mul_f32_e32 v90, v59, v90
	v_mul_f32_e32 v91, v59, v91
	v_sub_f32_e32 v6, v6, v88
	v_sub_f32_e32 v7, v7, v89
	v_sub_f32_e32 v8, v8, v90
	v_sub_f32_e32 v9, v9, v91
	v_fma_f32 v214, v197, v6, -v204
	v_fma_f32 v215, v197, v7, -v205
	v_fma_f32 v216, v197, v8, -v206
	v_fma_f32 v217, v197, v9, -v207
	v_mul_f32_e32 v214, v2, v214
	v_mul_f32_e32 v215, v3, v215
	v_mul_f32_e32 v216, v4, v216
	v_mul_f32_e32 v217, v5, v217
	v_cvt_pk_bf16_f32 v218, v214, v215
	v_cvt_pk_bf16_f32 v219, v216, v217
	global_store_dwordx2 v[24:25], v[218:219], off offset:2048 sc1
	s_mov_b64 s[0:1], 0x1000
	v_lshl_add_u64 v[24:25], v[24:25], 0, s[0:1]
	s_waitcnt vmcnt(31)
	v_lshlrev_b32_e32 v200, 16, v144
	v_and_b32_e32 v201, 0xffff0000, v144
	v_lshlrev_b32_e32 v202, 16, v145
	v_and_b32_e32 v203, 0xffff0000, v145
	v_mul_f32_e32 v204, v62, v200
	v_mul_f32_e32 v205, v62, v201
	v_mul_f32_e32 v206, v62, v202
	v_mul_f32_e32 v207, v62, v203
	v_fma_f32 v6, v62, v200, v6
	v_fma_f32 v7, v62, v201, v7
	v_fma_f32 v8, v62, v202, v8
	v_fma_f32 v9, v62, v203, v9
	v_lshlrev_b32_e32 v88, 16, v140
	v_and_b32_e32 v89, 0xffff0000, v140
	v_lshlrev_b32_e32 v90, 16, v141
	v_and_b32_e32 v91, 0xffff0000, v141
	v_mul_f32_e32 v88, v60, v88
	v_mul_f32_e32 v89, v60, v89
	v_mul_f32_e32 v90, v60, v90
	v_mul_f32_e32 v91, v60, v91
	v_sub_f32_e32 v6, v6, v88
	v_sub_f32_e32 v7, v7, v89
	v_sub_f32_e32 v8, v8, v90
	v_sub_f32_e32 v9, v9, v91
	v_fma_f32 v214, v197, v6, -v204
	v_fma_f32 v215, v197, v7, -v205
	v_fma_f32 v216, v197, v8, -v206
	v_fma_f32 v217, v197, v9, -v207
	v_mul_f32_e32 v214, v2, v214
	v_mul_f32_e32 v215, v3, v215
	v_mul_f32_e32 v216, v4, v216
	v_mul_f32_e32 v217, v5, v217
	v_cvt_pk_bf16_f32 v218, v214, v215
	v_cvt_pk_bf16_f32 v219, v216, v217
	global_store_dwordx2 v[24:25], v[218:219], off sc1
	s_waitcnt vmcnt(31)
	v_lshlrev_b32_e32 v200, 16, v146
	v_and_b32_e32 v201, 0xffff0000, v146
	v_lshlrev_b32_e32 v202, 16, v147
	v_and_b32_e32 v203, 0xffff0000, v147
	v_mul_f32_e32 v204, v63, v200
	v_mul_f32_e32 v205, v63, v201
	v_mul_f32_e32 v206, v63, v202
	v_mul_f32_e32 v207, v63, v203
	v_fma_f32 v6, v63, v200, v6
	v_fma_f32 v7, v63, v201, v7
	v_fma_f32 v8, v63, v202, v8
	v_fma_f32 v9, v63, v203, v9
	v_lshlrev_b32_e32 v88, 16, v142
	v_and_b32_e32 v89, 0xffff0000, v142
	v_lshlrev_b32_e32 v90, 16, v143
	v_and_b32_e32 v91, 0xffff0000, v143
	v_mul_f32_e32 v88, v61, v88
	v_mul_f32_e32 v89, v61, v89
	v_mul_f32_e32 v90, v61, v90
	v_mul_f32_e32 v91, v61, v91
	v_sub_f32_e32 v6, v6, v88
	v_sub_f32_e32 v7, v7, v89
	v_sub_f32_e32 v8, v8, v90
	v_sub_f32_e32 v9, v9, v91
	v_fma_f32 v214, v197, v6, -v204
	v_fma_f32 v215, v197, v7, -v205
	v_fma_f32 v216, v197, v8, -v206
	v_fma_f32 v217, v197, v9, -v207
	v_mul_f32_e32 v214, v2, v214
	v_mul_f32_e32 v215, v3, v215
	v_mul_f32_e32 v216, v4, v216
	v_mul_f32_e32 v217, v5, v217
	v_cvt_pk_bf16_f32 v218, v214, v215
	v_cvt_pk_bf16_f32 v219, v216, v217
	global_store_dwordx2 v[24:25], v[218:219], off offset:2048 sc1
	s_mov_b64 s[0:1], 0x1000
	v_lshl_add_u64 v[24:25], v[24:25], 0, s[0:1]
	s_waitcnt vmcnt(31)
	v_lshlrev_b32_e32 v200, 16, v148
	v_and_b32_e32 v201, 0xffff0000, v148
	v_lshlrev_b32_e32 v202, 16, v149
	v_and_b32_e32 v203, 0xffff0000, v149
	v_mul_f32_e32 v204, v64, v200
	v_mul_f32_e32 v205, v64, v201
	v_mul_f32_e32 v206, v64, v202
	v_mul_f32_e32 v207, v64, v203
	v_fma_f32 v6, v64, v200, v6
	v_fma_f32 v7, v64, v201, v7
	v_fma_f32 v8, v64, v202, v8
	v_fma_f32 v9, v64, v203, v9
	v_lshlrev_b32_e32 v88, 16, v144
	v_and_b32_e32 v89, 0xffff0000, v144
	v_lshlrev_b32_e32 v90, 16, v145
	v_and_b32_e32 v91, 0xffff0000, v145
	v_mul_f32_e32 v88, v62, v88
	v_mul_f32_e32 v89, v62, v89
	v_mul_f32_e32 v90, v62, v90
	v_mul_f32_e32 v91, v62, v91
	v_sub_f32_e32 v6, v6, v88
	v_sub_f32_e32 v7, v7, v89
	v_sub_f32_e32 v8, v8, v90
	v_sub_f32_e32 v9, v9, v91
	v_fma_f32 v214, v197, v6, -v204
	v_fma_f32 v215, v197, v7, -v205
	v_fma_f32 v216, v197, v8, -v206
	v_fma_f32 v217, v197, v9, -v207
	v_mul_f32_e32 v214, v2, v214
	v_mul_f32_e32 v215, v3, v215
	v_mul_f32_e32 v216, v4, v216
	v_mul_f32_e32 v217, v5, v217
	v_cvt_pk_bf16_f32 v218, v214, v215
	v_cvt_pk_bf16_f32 v219, v216, v217
	global_store_dwordx2 v[24:25], v[218:219], off sc1
	s_waitcnt vmcnt(31)
	v_lshlrev_b32_e32 v200, 16, v150
	v_and_b32_e32 v201, 0xffff0000, v150
	v_lshlrev_b32_e32 v202, 16, v151
	v_and_b32_e32 v203, 0xffff0000, v151
	v_mul_f32_e32 v204, v65, v200
	v_mul_f32_e32 v205, v65, v201
	v_mul_f32_e32 v206, v65, v202
	v_mul_f32_e32 v207, v65, v203
	v_fma_f32 v6, v65, v200, v6
	v_fma_f32 v7, v65, v201, v7
	v_fma_f32 v8, v65, v202, v8
	v_fma_f32 v9, v65, v203, v9
	v_lshlrev_b32_e32 v88, 16, v146
	v_and_b32_e32 v89, 0xffff0000, v146
	v_lshlrev_b32_e32 v90, 16, v147
	v_and_b32_e32 v91, 0xffff0000, v147
	v_mul_f32_e32 v88, v63, v88
	v_mul_f32_e32 v89, v63, v89
	v_mul_f32_e32 v90, v63, v90
	v_mul_f32_e32 v91, v63, v91
	v_sub_f32_e32 v6, v6, v88
	v_sub_f32_e32 v7, v7, v89
	v_sub_f32_e32 v8, v8, v90
	v_sub_f32_e32 v9, v9, v91
	v_fma_f32 v214, v197, v6, -v204
	v_fma_f32 v215, v197, v7, -v205
	v_fma_f32 v216, v197, v8, -v206
	v_fma_f32 v217, v197, v9, -v207
	v_mul_f32_e32 v214, v2, v214
	v_mul_f32_e32 v215, v3, v215
	v_mul_f32_e32 v216, v4, v216
	v_mul_f32_e32 v217, v5, v217
	v_cvt_pk_bf16_f32 v218, v214, v215
	v_cvt_pk_bf16_f32 v219, v216, v217
	global_store_dwordx2 v[24:25], v[218:219], off offset:2048 sc1
	s_mov_b64 s[0:1], 0x1000
	v_lshl_add_u64 v[24:25], v[24:25], 0, s[0:1]
	s_waitcnt vmcnt(31)
; __device__ __forceinline__ unsigned pk2(float lo, float hi) { return pg8::cvt_pk_bf16(lo, hi); }
; __device__ __forceinline__ f32x4 ld4bf(const bf16* p) { const v2u w = *(const v2u*)p; return (f32x4){bf_lo(w.x), bf_hi(w.x), bf_lo(w.y), bf_hi(w.y)}; }
; __device__ __forceinline__ void pool_prep(const bf16* X, const float* ss, const float* gain, bf16* PB, LAS unsigned char* lds, int vcu, int G, int tid) {
;     ...
;         for (int i = 0; i < 32; ++i) { const int row = ra + i, t = row - bstart;
;             const f32x4 xn = ld4bf(xp + (size_t)row * DM) * rsl[row - r0 + 16];
;             f32x4 old = {0.f, 0.f, 0.f, 0.f};
;             if (t >= w) old = ld4bf(xp + (size_t)(row - w) * DM) * rsl[row - w - r0 + 16];
;             S = S + xn - old;
;             const int cnt = (t + 1 < w) ? t + 1 : w;
;             const f32x4 p = (S * (1.0f / (float)cnt) - xn) * gn;
;             v2u o; o.x = pk2(p[0], p[1]); o.y = pk2(p[2], p[3]); *(v2u*)(PB + (size_t)row * DM + 4 * q) = o; }
	v_lshlrev_b32_e32 v200, 16, v152
	v_and_b32_e32 v201, 0xffff0000, v152
	v_lshlrev_b32_e32 v202, 16, v153
	v_and_b32_e32 v203, 0xffff0000, v153
	v_mul_f32_e32 v204, v66, v200
	v_mul_f32_e32 v205, v66, v201
	v_mul_f32_e32 v206, v66, v202
	v_mul_f32_e32 v207, v66, v203
	v_fma_f32 v6, v66, v200, v6
	v_fma_f32 v7, v66, v201, v7
	v_fma_f32 v8, v66, v202, v8
	v_fma_f32 v9, v66, v203, v9
	v_lshlrev_b32_e32 v88, 16, v148
	v_and_b32_e32 v89, 0xffff0000, v148
	v_lshlrev_b32_e32 v90, 16, v149
	v_and_b32_e32 v91, 0xffff0000, v149
	v_mul_f32_e32 v88, v64, v88
	v_mul_f32_e32 v89, v64, v89
	v_mul_f32_e32 v90, v64, v90
	v_mul_f32_e32 v91, v64, v91
	v_sub_f32_e32 v6, v6, v88
	v_sub_f32_e32 v7, v7, v89
	v_sub_f32_e32 v8, v8, v90
	v_sub_f32_e32 v9, v9, v91
	v_fma_f32 v214, v197, v6, -v204
	v_fma_f32 v215, v197, v7, -v205
	v_fma_f32 v216, v197, v8, -v206
	v_fma_f32 v217, v197, v9, -v207
	v_mul_f32_e32 v214, v2, v214
	v_mul_f32_e32 v215, v3, v215
	v_mul_f32_e32 v216, v4, v216
	v_mul_f32_e32 v217, v5, v217
	v_cvt_pk_bf16_f32 v218, v214, v215
	v_cvt_pk_bf16_f32 v219, v216, v217
	global_store_dwordx2 v[24:25], v[218:219], off sc1
	s_waitcnt vmcnt(31)
	v_lshlrev_b32_e32 v200, 16, v154
	v_and_b32_e32 v201, 0xffff0000, v154
	v_lshlrev_b32_e32 v202, 16, v155
	v_and_b32_e32 v203, 0xffff0000, v155
	v_mul_f32_e32 v204, v67, v200
	v_mul_f32_e32 v205, v67, v201
	v_mul_f32_e32 v206, v67, v202
	v_mul_f32_e32 v207, v67, v203
	v_fma_f32 v6, v67, v200, v6
	v_fma_f32 v7, v67, v201, v7
	v_fma_f32 v8, v67, v202, v8
	v_fma_f32 v9, v67, v203, v9
	v_lshlrev_b32_e32 v88, 16, v150
	v_and_b32_e32 v89, 0xffff0000, v150
	v_lshlrev_b32_e32 v90, 16, v151
	v_and_b32_e32 v91, 0xffff0000, v151
	v_mul_f32_e32 v88, v65, v88
	v_mul_f32_e32 v89, v65, v89
	v_mul_f32_e32 v90, v65, v90
	v_mul_f32_e32 v91, v65, v91
	v_sub_f32_e32 v6, v6, v88
	v_sub_f32_e32 v7, v7, v89
	v_sub_f32_e32 v8, v8, v90
	v_sub_f32_e32 v9, v9, v91
	v_fma_f32 v214, v197, v6, -v204
	v_fma_f32 v215, v197, v7, -v205
	v_fma_f32 v216, v197, v8, -v206
	v_fma_f32 v217, v197, v9, -v207
	v_mul_f32_e32 v214, v2, v214
	v_mul_f32_e32 v215, v3, v215
	v_mul_f32_e32 v216, v4, v216
	v_mul_f32_e32 v217, v5, v217
	v_cvt_pk_bf16_f32 v218, v214, v215
	v_cvt_pk_bf16_f32 v219, v216, v217
	global_store_dwordx2 v[24:25], v[218:219], off offset:2048 sc1
	s_mov_b64 s[0:1], 0x1000
	v_lshl_add_u64 v[24:25], v[24:25], 0, s[0:1]
	s_waitcnt vmcnt(31)
	v_lshlrev_b32_e32 v200, 16, v156
	v_and_b32_e32 v201, 0xffff0000, v156
	v_lshlrev_b32_e32 v202, 16, v157
	v_and_b32_e32 v203, 0xffff0000, v157
	v_mul_f32_e32 v204, v68, v200
	v_mul_f32_e32 v205, v68, v201
	v_mul_f32_e32 v206, v68, v202
	v_mul_f32_e32 v207, v68, v203
	v_fma_f32 v6, v68, v200, v6
	v_fma_f32 v7, v68, v201, v7
	v_fma_f32 v8, v68, v202, v8
	v_fma_f32 v9, v68, v203, v9
	v_lshlrev_b32_e32 v88, 16, v152
	v_and_b32_e32 v89, 0xffff0000, v152
	v_lshlrev_b32_e32 v90, 16, v153
	v_and_b32_e32 v91, 0xffff0000, v153
	v_mul_f32_e32 v88, v66, v88
	v_mul_f32_e32 v89, v66, v89
	v_mul_f32_e32 v90, v66, v90
	v_mul_f32_e32 v91, v66, v91
	v_sub_f32_e32 v6, v6, v88
	v_sub_f32_e32 v7, v7, v89
	v_sub_f32_e32 v8, v8, v90
	v_sub_f32_e32 v9, v9, v91
	v_fma_f32 v214, v197, v6, -v204
	v_fma_f32 v215, v197, v7, -v205
	v_fma_f32 v216, v197, v8, -v206
	v_fma_f32 v217, v197, v9, -v207
	v_mul_f32_e32 v214, v2, v214
	v_mul_f32_e32 v215, v3, v215
	v_mul_f32_e32 v216, v4, v216
	v_mul_f32_e32 v217, v5, v217
	v_cvt_pk_bf16_f32 v218, v214, v215
	v_cvt_pk_bf16_f32 v219, v216, v217
	global_store_dwordx2 v[24:25], v[218:219], off sc1
	s_waitcnt vmcnt(31)
	v_lshlrev_b32_e32 v200, 16, v158
	v_and_b32_e32 v201, 0xffff0000, v158
	v_lshlrev_b32_e32 v202, 16, v159
	v_and_b32_e32 v203, 0xffff0000, v159
	v_mul_f32_e32 v204, v69, v200
	v_mul_f32_e32 v205, v69, v201
	v_mul_f32_e32 v206, v69, v202
	v_mul_f32_e32 v207, v69, v203
	v_fma_f32 v6, v69, v200, v6
	v_fma_f32 v7, v69, v201, v7
	v_fma_f32 v8, v69, v202, v8
	v_fma_f32 v9, v69, v203, v9
	v_lshlrev_b32_e32 v88, 16, v154
	v_and_b32_e32 v89, 0xffff0000, v154
	v_lshlrev_b32_e32 v90, 16, v155
	v_and_b32_e32 v91, 0xffff0000, v155
	v_mul_f32_e32 v88, v67, v88
	v_mul_f32_e32 v89, v67, v89
	v_mul_f32_e32 v90, v67, v90
	v_mul_f32_e32 v91, v67, v91
	v_sub_f32_e32 v6, v6, v88
	v_sub_f32_e32 v7, v7, v89
	v_sub_f32_e32 v8, v8, v90
	v_sub_f32_e32 v9, v9, v91
	v_fma_f32 v214, v197, v6, -v204
	v_fma_f32 v215, v197, v7, -v205
	v_fma_f32 v216, v197, v8, -v206
	v_fma_f32 v217, v197, v9, -v207
	v_mul_f32_e32 v214, v2, v214
	v_mul_f32_e32 v215, v3, v215
	v_mul_f32_e32 v216, v4, v216
	v_mul_f32_e32 v217, v5, v217
	v_cvt_pk_bf16_f32 v218, v214, v215
	v_cvt_pk_bf16_f32 v219, v216, v217
	global_store_dwordx2 v[24:25], v[218:219], off offset:2048 sc1
	s_mov_b64 s[0:1], 0x1000
	v_lshl_add_u64 v[24:25], v[24:25], 0, s[0:1]
	s_waitcnt vmcnt(31)
; __device__ __forceinline__ unsigned pk2(float lo, float hi) { return pg8::cvt_pk_bf16(lo, hi); }
; __device__ __forceinline__ f32x4 ld4bf(const bf16* p) { const v2u w = *(const v2u*)p; return (f32x4){bf_lo(w.x), bf_hi(w.x), bf_lo(w.y), bf_hi(w.y)}; }
; __device__ __forceinline__ void pool_prep(const bf16* X, const float* ss, const float* gain, bf16* PB, LAS unsigned char* lds, int vcu, int G, int tid) {
;     ...
;         for (int i = 0; i < 32; ++i) { const int row = ra + i, t = row - bstart;
;             const f32x4 xn = ld4bf(xp + (size_t)row * DM) * rsl[row - r0 + 16];
;             f32x4 old = {0.f, 0.f, 0.f, 0.f};
;             if (t >= w) old = ld4bf(xp + (size_t)(row - w) * DM) * rsl[row - w - r0 + 16];
;             S = S + xn - old;
;             const int cnt = (t + 1 < w) ? t + 1 : w;
;             const f32x4 p = (S * (1.0f / (float)cnt) - xn) * gn;
;             v2u o; o.x = pk2(p[0], p[1]); o.y = pk2(p[2], p[3]); *(v2u*)(PB + (size_t)row * DM + 4 * q) = o; }
	v_lshlrev_b32_e32 v200, 16, v160
	v_and_b32_e32 v201, 0xffff0000, v160
	v_lshlrev_b32_e32 v202, 16, v161
	v_and_b32_e32 v203, 0xffff0000, v161
	v_mul_f32_e32 v204, v70, v200
	v_mul_f32_e32 v205, v70, v201
	v_mul_f32_e32 v206, v70, v202
	v_mul_f32_e32 v207, v70, v203
	v_fma_f32 v6, v70, v200, v6
	v_fma_f32 v7, v70, v201, v7
	v_fma_f32 v8, v70, v202, v8
	v_fma_f32 v9, v70, v203, v9
	v_lshlrev_b32_e32 v88, 16, v156
	v_and_b32_e32 v89, 0xffff0000, v156
	v_lshlrev_b32_e32 v90, 16, v157
	v_and_b32_e32 v91, 0xffff0000, v157
	v_mul_f32_e32 v88, v68, v88
	v_mul_f32_e32 v89, v68, v89
	v_mul_f32_e32 v90, v68, v90
	v_mul_f32_e32 v91, v68, v91
	v_sub_f32_e32 v6, v6, v88
	v_sub_f32_e32 v7, v7, v89
	v_sub_f32_e32 v8, v8, v90
	v_sub_f32_e32 v9, v9, v91
	v_fma_f32 v214, v197, v6, -v204
	v_fma_f32 v215, v197, v7, -v205
	v_fma_f32 v216, v197, v8, -v206
	v_fma_f32 v217, v197, v9, -v207
	v_mul_f32_e32 v214, v2, v214
	v_mul_f32_e32 v215, v3, v215
	v_mul_f32_e32 v216, v4, v216
	v_mul_f32_e32 v217, v5, v217
	v_cvt_pk_bf16_f32 v218, v214, v215
	v_cvt_pk_bf16_f32 v219, v216, v217
	global_store_dwordx2 v[24:25], v[218:219], off sc1
	s_waitcnt vmcnt(31)
	v_lshlrev_b32_e32 v200, 16, v162
	v_and_b32_e32 v201, 0xffff0000, v162
	v_lshlrev_b32_e32 v202, 16, v163
	v_and_b32_e32 v203, 0xffff0000, v163
	v_mul_f32_e32 v204, v71, v200
	v_mul_f32_e32 v205, v71, v201
	v_mul_f32_e32 v206, v71, v202
	v_mul_f32_e32 v207, v71, v203
	v_fma_f32 v6, v71, v200, v6
	v_fma_f32 v7, v71, v201, v7
	v_fma_f32 v8, v71, v202, v8
	v_fma_f32 v9, v71, v203, v9
	v_lshlrev_b32_e32 v88, 16, v158
	v_and_b32_e32 v89, 0xffff0000, v158
	v_lshlrev_b32_e32 v90, 16, v159
	v_and_b32_e32 v91, 0xffff0000, v159
	v_mul_f32_e32 v88, v69, v88
	v_mul_f32_e32 v89, v69, v89
	v_mul_f32_e32 v90, v69, v90
	v_mul_f32_e32 v91, v69, v91
	v_sub_f32_e32 v6, v6, v88
	v_sub_f32_e32 v7, v7, v89
	v_sub_f32_e32 v8, v8, v90
	v_sub_f32_e32 v9, v9, v91
	v_fma_f32 v214, v197, v6, -v204
	v_fma_f32 v215, v197, v7, -v205
	v_fma_f32 v216, v197, v8, -v206
	v_fma_f32 v217, v197, v9, -v207
	v_mul_f32_e32 v214, v2, v214
	v_mul_f32_e32 v215, v3, v215
	v_mul_f32_e32 v216, v4, v216
	v_mul_f32_e32 v217, v5, v217
	v_cvt_pk_bf16_f32 v218, v214, v215
	v_cvt_pk_bf16_f32 v219, v216, v217
	global_store_dwordx2 v[24:25], v[218:219], off offset:2048 sc1
	s_mov_b64 s[0:1], 0x1000
	v_lshl_add_u64 v[24:25], v[24:25], 0, s[0:1]
	s_waitcnt vmcnt(31)
	v_lshlrev_b32_e32 v200, 16, v164
	v_and_b32_e32 v201, 0xffff0000, v164
	v_lshlrev_b32_e32 v202, 16, v165
	v_and_b32_e32 v203, 0xffff0000, v165
	v_mul_f32_e32 v204, v72, v200
	v_mul_f32_e32 v205, v72, v201
	v_mul_f32_e32 v206, v72, v202
	v_mul_f32_e32 v207, v72, v203
	v_fma_f32 v6, v72, v200, v6
	v_fma_f32 v7, v72, v201, v7
	v_fma_f32 v8, v72, v202, v8
	v_fma_f32 v9, v72, v203, v9
	v_lshlrev_b32_e32 v88, 16, v160
	v_and_b32_e32 v89, 0xffff0000, v160
	v_lshlrev_b32_e32 v90, 16, v161
	v_and_b32_e32 v91, 0xffff0000, v161
	v_mul_f32_e32 v88, v70, v88
	v_mul_f32_e32 v89, v70, v89
	v_mul_f32_e32 v90, v70, v90
	v_mul_f32_e32 v91, v70, v91
	v_sub_f32_e32 v6, v6, v88
	v_sub_f32_e32 v7, v7, v89
	v_sub_f32_e32 v8, v8, v90
	v_sub_f32_e32 v9, v9, v91
	v_fma_f32 v214, v197, v6, -v204
	v_fma_f32 v215, v197, v7, -v205
	v_fma_f32 v216, v197, v8, -v206
	v_fma_f32 v217, v197, v9, -v207
	v_mul_f32_e32 v214, v2, v214
	v_mul_f32_e32 v215, v3, v215
	v_mul_f32_e32 v216, v4, v216
	v_mul_f32_e32 v217, v5, v217
	v_cvt_pk_bf16_f32 v218, v214, v215
	v_cvt_pk_bf16_f32 v219, v216, v217
	global_store_dwordx2 v[24:25], v[218:219], off sc1
	s_waitcnt vmcnt(31)
	v_lshlrev_b32_e32 v200, 16, v166
	v_and_b32_e32 v201, 0xffff0000, v166
	v_lshlrev_b32_e32 v202, 16, v167
	v_and_b32_e32 v203, 0xffff0000, v167
	v_mul_f32_e32 v204, v73, v200
	v_mul_f32_e32 v205, v73, v201
	v_mul_f32_e32 v206, v73, v202
	v_mul_f32_e32 v207, v73, v203
	v_fma_f32 v6, v73, v200, v6
	v_fma_f32 v7, v73, v201, v7
	v_fma_f32 v8, v73, v202, v8
	v_fma_f32 v9, v73, v203, v9
	v_lshlrev_b32_e32 v88, 16, v162
	v_and_b32_e32 v89, 0xffff0000, v162
	v_lshlrev_b32_e32 v90, 16, v163
	v_and_b32_e32 v91, 0xffff0000, v163
	v_mul_f32_e32 v88, v71, v88
	v_mul_f32_e32 v89, v71, v89
	v_mul_f32_e32 v90, v71, v90
	v_mul_f32_e32 v91, v71, v91
	v_sub_f32_e32 v6, v6, v88
	v_sub_f32_e32 v7, v7, v89
	v_sub_f32_e32 v8, v8, v90
	v_sub_f32_e32 v9, v9, v91
	v_fma_f32 v214, v197, v6, -v204
	v_fma_f32 v215, v197, v7, -v205
	v_fma_f32 v216, v197, v8, -v206
	v_fma_f32 v217, v197, v9, -v207
	v_mul_f32_e32 v214, v2, v214
	v_mul_f32_e32 v215, v3, v215
	v_mul_f32_e32 v216, v4, v216
	v_mul_f32_e32 v217, v5, v217
	v_cvt_pk_bf16_f32 v218, v214, v215
	v_cvt_pk_bf16_f32 v219, v216, v217
	global_store_dwordx2 v[24:25], v[218:219], off offset:2048 sc1
	s_branch .LBB0_308
	s_nop 0
	s_nop 0
	s_nop 0
	s_nop 0
	s_nop 0
	s_nop 0
	s_nop 0
	s_nop 0
	s_nop 0
	s_nop 0
